# speedup vs baseline: 1.0055x; 1.0055x over previous
; DI unsigned pk_bf16(float lo, float hi) { f32x2_t v = {lo, hi}; return __builtin_bit_cast(unsigned, __builtin_convertvector(v, bf16x2_t)); }
; DI float bflo(unsigned u) { return __uint_as_float(u << 16); }
; DI float bfhi(unsigned u) { return __uint_as_float(u & 0xffff0000u); }
; DI float fgelu(float x) { return x * fsigmoid(1.5957691216057308f * (x + 0.044715f * x * x * x)); }
; DI void conv8(const u32x4& v0, const u32x4& v1, const u32x4& v2, const u32x4& g0, const u32x4& g1, const u32x4& g2,
;               const float (&wv)[3][8], const float (&wg)[3][8], const float (&bv)[8], const float (&bg)[8], u32x4& o) {
;     ...
;   for (int e = 0; e < 4; ++e) {
;     const float cv0 = bv[2 * e] + wv[0][2 * e] * bflo(v2[e]) + wv[1][2 * e] * bflo(v1[e]) + wv[2][2 * e] * bflo(v0[e]);
;     const float cv1 = bv[2 * e + 1] + wv[0][2 * e + 1] * bfhi(v2[e]) + wv[1][2 * e + 1] * bfhi(v1[e]) + wv[2][2 * e + 1] * bfhi(v0[e]);
;     const float cg0 = bg[2 * e] + wg[0][2 * e] * bflo(g2[e]) + wg[1][2 * e] * bflo(g1[e]) + wg[2][2 * e] * bflo(g0[e]);
;     const float cg1 = bg[2 * e + 1] + wg[0][2 * e + 1] * bfhi(g2[e]) + wg[1][2 * e + 1] * bfhi(g1[e]) + wg[2][2 * e + 1] * bfhi(g0[e]);
;     o[e] = pk_bf16(fgelu(cg0) * cv0, fgelu(cg1) * cv1);
;   }
; DI void p8_phase(const Params& p, int layer, char* lds) {
;     ...
; #pragma unroll 2
;         for (int i = 0; i < 8; ++i) {
;           const int t = (tid >> 4) + 32 * i;
;           const u32x4 v0 = TLD(t, 0), g0 = TLD(t, 1);
;           if (t >= 2) {
;             const u32x4 v1 = TLD(t - 1, 0), g1 = TLD(t - 1, 1), v2 = TLD(t - 2, 0), g2 = TLD(t - 2, 1);
;             u32x4 o; conv8(v0, v1, v2, g0, g1, g2, wv, wg, bv, bg, o);
;             *(u32x4*)(hb + (size_t)t * DFF) = o;
;           }
;           if (t < 2 || t >= 254) {
;             const int slot = (t < 2) ? t : t - 252;
;             *(u32x4*)(upe + (size_t)(slot * 2) * DFF) = v0;
;             *(u32x4*)(upe + (size_t)(slot * 2 + 1) * DFF) = g0;
;           }
.LBB0_1177:
	v_add_u32_e32 v100, s7, v99
	v_add_u32_e32 v101, s7, v98
	s_waitcnt lgkmcnt(1)
	ds_read_b128 v[70:73], v100
	s_waitcnt lgkmcnt(1)
	ds_read_b128 v[66:69], v101
	v_cmp_lt_i32_e32 vcc, 1, v64
	s_and_saveexec_b64 s[8:9], vcc
	s_cbranch_execz .LBB0_1179
	v_add_u32_e32 v74, 0xffffffbe, v96
	v_add_u32_e32 v78, 0xffffffbc, v96
	v_bitop3_b32 v75, v74, v94, 14 bitop3:0x6c
	v_bitop3_b32 v79, v78, v94, 14 bitop3:0x6c
	v_lshlrev_b32_e32 v75, 3, v75
	v_lshlrev_b32_e32 v79, 3, v79
	v_add3_u32 v75, v97, v75, s7
	v_add3_u32 v79, v97, v79, s7
	v_add_u32_e32 v75, 0xfffffe00, v75
	v_bitop3_b32 v74, v74, v95, 14 bitop3:0x6c
	v_add_u32_e32 v79, 0xfffffc00, v79
	v_bitop3_b32 v78, v78, v95, 14 bitop3:0x6c
	ds_read_b128 v[82:85], v75
	ds_read_b128 v[86:89], v79
	v_lshlrev_b32_e32 v74, 3, v74
	v_lshlrev_b32_e32 v78, 3, v78
	v_add3_u32 v74, v97, v74, s7
	v_add3_u32 v78, v97, v78, s7
	v_add_u32_e32 v74, 0xfffffe00, v74
	v_add_u32_e32 v78, 0xfffffc00, v78
	ds_read_b128 v[74:77], v74
	ds_read_b128 v[78:81], v78
	s_waitcnt lgkmcnt(2)
	v_lshlrev_b32_e32 v102, 16, v86
	v_and_b32_e32 v103, 0xffff0000, v86
	v_pk_fma_f32 v[102:103], v[20:21], v[102:103], v[60:61]
	v_lshlrev_b32_e32 v104, 16, v82
	v_and_b32_e32 v105, 0xffff0000, v82
	v_lshlrev_b32_e32 v86, 16, v87
	v_and_b32_e32 v87, 0xffff0000, v87
	v_pk_fma_f32 v[102:103], v[24:25], v[104:105], v[102:103]
	v_lshlrev_b32_e32 v104, 16, v70
	v_and_b32_e32 v105, 0xffff0000, v70
	v_pk_fma_f32 v[86:87], v[22:23], v[86:87], v[62:63]
	v_lshlrev_b32_e32 v82, 16, v83
	v_and_b32_e32 v83, 0xffff0000, v83
	v_pk_fma_f32 v[102:103], v[40:41], v[104:105], v[102:103]
	s_waitcnt lgkmcnt(0)
	v_lshlrev_b32_e32 v104, 16, v78
	v_and_b32_e32 v105, 0xffff0000, v78
	v_pk_fma_f32 v[82:83], v[26:27], v[82:83], v[86:87]
	v_lshlrev_b32_e32 v86, 16, v71
	v_and_b32_e32 v87, 0xffff0000, v71
	v_lshlrev_b32_e32 v78, 16, v79
	v_and_b32_e32 v79, 0xffff0000, v79
	v_pk_fma_f32 v[82:83], v[42:43], v[86:87], v[82:83]
	v_pk_fma_f32 v[78:79], v[2:3], v[78:79], v[10:11]
	v_lshlrev_b32_e32 v86, 16, v75
	v_and_b32_e32 v87, 0xffff0000, v75
	v_pk_fma_f32 v[78:79], v[30:31], v[86:87], v[78:79]
	v_lshlrev_b32_e32 v86, 16, v67
	v_and_b32_e32 v87, 0xffff0000, v67
	v_pk_fma_f32 v[78:79], v[46:47], v[86:87], v[78:79]
	v_pk_fma_f32 v[104:105], v[0:1], v[104:105], v[8:9]
	v_mul_f32_e32 v75, 0x3d372713, v78
	v_mul_f32_e32 v75, v78, v75
	v_fma_f32 v75, v78, v75, v78
	v_mul_f32_e32 v75, 0x3fcc422a, v75
	v_mul_f32_e32 v75, 0xbfb8aa3b, v75
	v_exp_f32_e32 v75, v75
	v_lshlrev_b32_e32 v106, 16, v74
	v_and_b32_e32 v107, 0xffff0000, v74
	v_pk_fma_f32 v[104:105], v[28:29], v[106:107], v[104:105]
	v_add_f32_e32 v75, 1.0, v75
	v_rcp_f32_e32 v86, v75
	v_mul_f32_e32 v75, 0x3d372713, v79
	v_mul_f32_e32 v75, v79, v75
	v_fma_f32 v75, v79, v75, v79
	v_mul_f32_e32 v75, 0x3fcc422a, v75
	v_mul_f32_e32 v75, 0xbfb8aa3b, v75
	v_exp_f32_e32 v75, v75
	v_lshlrev_b32_e32 v106, 16, v66
	v_and_b32_e32 v107, 0xffff0000, v66
	v_pk_fma_f32 v[104:105], v[44:45], v[106:107], v[104:105]
	v_add_f32_e32 v75, 1.0, v75
	v_rcp_f32_e32 v87, v75
	v_mul_f32_e32 v74, 0x3d372713, v104
	v_mul_f32_e32 v74, v104, v74
	v_fma_f32 v74, v104, v74, v104
	v_pk_mul_f32 v[78:79], v[78:79], v[86:87]
	v_lshlrev_b32_e32 v86, 16, v76
	v_pk_mul_f32 v[78:79], v[82:83], v[78:79]
	v_lshlrev_b32_e32 v82, 16, v84
	v_cvt_pk_bf16_f32 v75, v78, v79
	v_lshlrev_b32_e32 v78, 16, v88
	v_and_b32_e32 v79, 0xffff0000, v88
	v_pk_fma_f32 v[78:79], v[16:17], v[78:79], v[56:57]
	v_and_b32_e32 v83, 0xffff0000, v84
	v_pk_fma_f32 v[78:79], v[32:33], v[82:83], v[78:79]
	v_lshlrev_b32_e32 v82, 16, v72
	v_and_b32_e32 v83, 0xffff0000, v72
	v_pk_fma_f32 v[78:79], v[48:49], v[82:83], v[78:79]
	v_lshlrev_b32_e32 v82, 16, v80
	v_and_b32_e32 v83, 0xffff0000, v80
	v_pk_fma_f32 v[82:83], v[4:5], v[82:83], v[12:13]
	v_and_b32_e32 v87, 0xffff0000, v76
	v_pk_fma_f32 v[82:83], v[36:37], v[86:87], v[82:83]
	v_lshlrev_b32_e32 v86, 16, v68
	v_and_b32_e32 v87, 0xffff0000, v68
	v_pk_fma_f32 v[82:83], v[52:53], v[86:87], v[82:83]
	v_lshlrev_b32_e32 v80, 16, v81
	v_mul_f32_e32 v76, 0x3d372713, v82
	v_mul_f32_e32 v76, v82, v76
	v_fma_f32 v76, v82, v76, v82
	v_mul_f32_e32 v76, 0x3fcc422a, v76
	v_mul_f32_e32 v76, 0xbfb8aa3b, v76
	v_exp_f32_e32 v76, v76
	v_and_b32_e32 v81, 0xffff0000, v81
	v_pk_fma_f32 v[80:81], v[6:7], v[80:81], v[14:15]
	v_mul_f32_e32 v74, 0x3fcc422a, v74
	v_add_f32_e32 v76, 1.0, v76
	v_rcp_f32_e32 v86, v76
	v_mul_f32_e32 v76, 0x3d372713, v83
	v_mul_f32_e32 v76, v83, v76
	v_fma_f32 v76, v83, v76, v83
	v_mul_f32_e32 v76, 0x3fcc422a, v76
	v_mul_f32_e32 v76, 0xbfb8aa3b, v76
	v_exp_f32_e32 v76, v76
	v_mul_f32_e32 v74, 0xbfb8aa3b, v74
	v_exp_f32_e32 v74, v74
	v_add_f32_e32 v76, 1.0, v76
	v_rcp_f32_e32 v87, v76
	v_add_f32_e32 v74, 1.0, v74
	v_rcp_f32_e32 v106, v74
	v_mul_f32_e32 v74, 0x3d372713, v105
	v_pk_mul_f32 v[82:83], v[82:83], v[86:87]
	v_mul_f32_e32 v74, v105, v74
	v_pk_mul_f32 v[78:79], v[78:79], v[82:83]
	v_lshlrev_b32_e32 v82, 16, v85
	v_cvt_pk_bf16_f32 v76, v78, v79
	v_lshlrev_b32_e32 v78, 16, v89
	v_and_b32_e32 v79, 0xffff0000, v89
	v_pk_fma_f32 v[78:79], v[18:19], v[78:79], v[58:59]
	v_and_b32_e32 v83, 0xffff0000, v85
	v_pk_fma_f32 v[78:79], v[34:35], v[82:83], v[78:79]
	v_lshlrev_b32_e32 v82, 16, v73
	v_and_b32_e32 v83, 0xffff0000, v73
	v_pk_fma_f32 v[78:79], v[50:51], v[82:83], v[78:79]
	v_lshlrev_b32_e32 v82, 16, v77
	v_and_b32_e32 v83, 0xffff0000, v77
	v_pk_fma_f32 v[80:81], v[38:39], v[82:83], v[80:81]
	v_lshlrev_b32_e32 v82, 16, v69
	v_and_b32_e32 v83, 0xffff0000, v69
	v_pk_fma_f32 v[80:81], v[54:55], v[82:83], v[80:81]
	v_fma_f32 v74, v105, v74, v105
	v_mul_f32_e32 v77, 0x3d372713, v80
	v_mul_f32_e32 v77, v80, v77
	v_fma_f32 v77, v80, v77, v80
	v_mul_f32_e32 v77, 0x3fcc422a, v77
	v_mul_f32_e32 v77, 0xbfb8aa3b, v77
	v_exp_f32_e32 v77, v77
	v_mul_f32_e32 v74, 0x3fcc422a, v74
	v_mul_f32_e32 v74, 0xbfb8aa3b, v74
	v_exp_f32_e32 v74, v74
	v_add_f32_e32 v77, 1.0, v77
	v_rcp_f32_e32 v82, v77
	v_mul_f32_e32 v77, 0x3d372713, v81
	v_mul_f32_e32 v77, v81, v77
	v_fma_f32 v77, v81, v77, v81
	v_mul_f32_e32 v77, 0x3fcc422a, v77
	v_mul_f32_e32 v77, 0xbfb8aa3b, v77
	v_exp_f32_e32 v77, v77
	v_add_f32_e32 v74, 1.0, v74
	v_rcp_f32_e32 v107, v74
	v_add_f32_e32 v77, 1.0, v77
	v_rcp_f32_e32 v83, v77
	v_pk_mul_f32 v[104:105], v[104:105], v[106:107]
	v_pk_mul_f32 v[80:81], v[80:81], v[82:83]
	v_pk_mul_f32 v[102:103], v[102:103], v[104:105]
	v_pk_mul_f32 v[78:79], v[78:79], v[80:81]
	v_cvt_pk_bf16_f32 v74, v102, v103
	v_cvt_pk_bf16_f32 v77, v78, v79
	v_mad_u64_u32 v[78:79], s[22:23], v64, s6, v[90:91]
	global_store_dwordx4 v[78:79], v[74:77], off sc0 sc1
; DI void p8_phase(const Params& p, int layer, char* lds) {
;     ...
;         for (int i = 0; i < 8; ++i) {
;           const int t = (tid >> 4) + 32 * i;
;           const u32x4 v0 = TLD(t, 0), g0 = TLD(t, 1);
;           if (t >= 2) {
;             const u32x4 v1 = TLD(t - 1, 0), g1 = TLD(t - 1, 1), v2 = TLD(t - 2, 0), g2 = TLD(t - 2, 1);
;             u32x4 o; conv8(v0, v1, v2, g0, g1, g2, wv, wg, bv, bg, o);
;             *(u32x4*)(hb + (size_t)t * DFF) = o;
;     ...
;           if (t < 2 || t >= 254) {
;             const int slot = (t < 2) ? t : t - 252;
;             *(u32x4*)(upe + (size_t)(slot * 2) * DFF) = v0;
;             *(u32x4*)(upe + (size_t)(slot * 2 + 1) * DFF) = g0;
;           }
.LBB0_1179:
	s_or_b64 exec, exec, s[8:9]
	s_nop 0
	v_add_u32_e32 v74, 0xffffff02, v64
	v_cmp_gt_u32_e32 vcc, s63, v74
	s_and_saveexec_b64 s[8:9], vcc
	s_cbranch_execz .LBB0_1181
	v_cmp_gt_i32_e32 vcc, 2, v64
	s_nop 1
	v_cndmask_b32_e32 v74, v251, v221, vcc
	v_add_u32_e32 v76, v96, v74
	v_mad_i64_i32 v[74:75], s[22:23], v76, s6, v[92:93]
	s_waitcnt lgkmcnt(1)
	global_store_dwordx4 v[74:75], v[70:73], off sc0 sc1
	s_nop 1
	v_or_b32_e32 v70, 1, v76
	v_mad_i64_i32 v[70:71], s[22:23], v70, s6, v[92:93]
	s_waitcnt lgkmcnt(0)
	global_store_dwordx4 v[70:71], v[66:69], off sc0 sc1
.LBB0_1181:
	s_or_b64 exec, exec, s[8:9]
	s_waitcnt lgkmcnt(1)
	ds_read_b128 v[70:73], v100 offset:16384
	s_waitcnt lgkmcnt(1)
	ds_read_b128 v[66:69], v101 offset:16384
	v_add_u32_e32 v100, 32, v64
	v_cmp_lt_i32_e32 vcc, 1, v100
	s_and_saveexec_b64 s[8:9], vcc
	s_cbranch_execz .LBB0_1183
	v_add_u32_e32 v74, -2, v96
	v_add_u32_e32 v78, -4, v96
	v_bitop3_b32 v75, v74, v94, 14 bitop3:0x6c
	v_bitop3_b32 v79, v78, v94, 14 bitop3:0x6c
	v_lshlrev_b32_e32 v75, 3, v75
	v_lshlrev_b32_e32 v79, 3, v79
	v_add3_u32 v75, v97, v75, s7
	v_add3_u32 v79, v97, v79, s7
	ds_read_b128 v[82:85], v75 offset:15872
	ds_read_b128 v[86:89], v79 offset:15360
	v_bitop3_b32 v74, v74, v95, 14 bitop3:0x6c
	v_bitop3_b32 v78, v78, v95, 14 bitop3:0x6c
	v_lshlrev_b32_e32 v74, 3, v74
	v_lshlrev_b32_e32 v78, 3, v78
	v_add3_u32 v74, v97, v74, s7
	v_add3_u32 v78, v97, v78, s7
	ds_read_b128 v[74:77], v74 offset:15872
	ds_read_b128 v[78:81], v78 offset:15360
	s_waitcnt lgkmcnt(2)
	v_lshlrev_b32_e32 v102, 16, v86
	v_and_b32_e32 v103, 0xffff0000, v86
	v_pk_fma_f32 v[102:103], v[20:21], v[102:103], v[60:61]
	v_lshlrev_b32_e32 v104, 16, v82
	v_and_b32_e32 v105, 0xffff0000, v82
	v_lshlrev_b32_e32 v86, 16, v87
	v_and_b32_e32 v87, 0xffff0000, v87
	v_pk_fma_f32 v[102:103], v[24:25], v[104:105], v[102:103]
	v_lshlrev_b32_e32 v104, 16, v70
	v_and_b32_e32 v105, 0xffff0000, v70
	v_pk_fma_f32 v[86:87], v[22:23], v[86:87], v[62:63]
	v_lshlrev_b32_e32 v82, 16, v83
	v_and_b32_e32 v83, 0xffff0000, v83
	v_pk_fma_f32 v[102:103], v[40:41], v[104:105], v[102:103]
	s_waitcnt lgkmcnt(0)
	v_lshlrev_b32_e32 v104, 16, v78
	v_and_b32_e32 v105, 0xffff0000, v78
	v_pk_fma_f32 v[82:83], v[26:27], v[82:83], v[86:87]
	v_lshlrev_b32_e32 v86, 16, v71
	v_and_b32_e32 v87, 0xffff0000, v71
	v_lshlrev_b32_e32 v78, 16, v79
	v_and_b32_e32 v79, 0xffff0000, v79
	v_pk_fma_f32 v[82:83], v[42:43], v[86:87], v[82:83]
	v_pk_fma_f32 v[78:79], v[2:3], v[78:79], v[10:11]
	v_lshlrev_b32_e32 v86, 16, v75
	v_and_b32_e32 v87, 0xffff0000, v75
	v_pk_fma_f32 v[78:79], v[30:31], v[86:87], v[78:79]
	v_lshlrev_b32_e32 v86, 16, v67
	v_and_b32_e32 v87, 0xffff0000, v67
	v_pk_fma_f32 v[78:79], v[46:47], v[86:87], v[78:79]
	v_pk_fma_f32 v[104:105], v[0:1], v[104:105], v[8:9]
	v_mul_f32_e32 v75, 0x3d372713, v78
	v_mul_f32_e32 v75, v78, v75
	v_fma_f32 v75, v78, v75, v78
	v_mul_f32_e32 v75, 0x3fcc422a, v75
	v_mul_f32_e32 v75, 0xbfb8aa3b, v75
	v_exp_f32_e32 v75, v75
	v_lshlrev_b32_e32 v106, 16, v74
	v_and_b32_e32 v107, 0xffff0000, v74
	v_pk_fma_f32 v[104:105], v[28:29], v[106:107], v[104:105]
	v_add_f32_e32 v75, 1.0, v75
	v_rcp_f32_e32 v86, v75
	v_mul_f32_e32 v75, 0x3d372713, v79
	v_mul_f32_e32 v75, v79, v75
	v_fma_f32 v75, v79, v75, v79
	v_mul_f32_e32 v75, 0x3fcc422a, v75
	v_mul_f32_e32 v75, 0xbfb8aa3b, v75
	v_exp_f32_e32 v75, v75
	v_lshlrev_b32_e32 v106, 16, v66
	v_and_b32_e32 v107, 0xffff0000, v66
	v_pk_fma_f32 v[104:105], v[44:45], v[106:107], v[104:105]
	v_add_f32_e32 v75, 1.0, v75
	v_rcp_f32_e32 v87, v75
	v_mul_f32_e32 v74, 0x3d372713, v104
	v_mul_f32_e32 v74, v104, v74
	v_fma_f32 v74, v104, v74, v104
	v_pk_mul_f32 v[78:79], v[78:79], v[86:87]
	v_lshlrev_b32_e32 v86, 16, v76
	v_pk_mul_f32 v[78:79], v[82:83], v[78:79]
	v_lshlrev_b32_e32 v82, 16, v84
	v_cvt_pk_bf16_f32 v75, v78, v79
	v_lshlrev_b32_e32 v78, 16, v88
	v_and_b32_e32 v79, 0xffff0000, v88
	v_pk_fma_f32 v[78:79], v[16:17], v[78:79], v[56:57]
	v_and_b32_e32 v83, 0xffff0000, v84
	v_pk_fma_f32 v[78:79], v[32:33], v[82:83], v[78:79]
	v_lshlrev_b32_e32 v82, 16, v72
	v_and_b32_e32 v83, 0xffff0000, v72
	v_pk_fma_f32 v[78:79], v[48:49], v[82:83], v[78:79]
	v_lshlrev_b32_e32 v82, 16, v80
	v_and_b32_e32 v83, 0xffff0000, v80
	v_pk_fma_f32 v[82:83], v[4:5], v[82:83], v[12:13]
	v_and_b32_e32 v87, 0xffff0000, v76
	v_pk_fma_f32 v[82:83], v[36:37], v[86:87], v[82:83]
	v_lshlrev_b32_e32 v86, 16, v68
	v_and_b32_e32 v87, 0xffff0000, v68
	v_pk_fma_f32 v[82:83], v[52:53], v[86:87], v[82:83]
	v_lshlrev_b32_e32 v80, 16, v81
	v_mul_f32_e32 v76, 0x3d372713, v82
	v_mul_f32_e32 v76, v82, v76
	v_fma_f32 v76, v82, v76, v82
	v_mul_f32_e32 v76, 0x3fcc422a, v76
	v_mul_f32_e32 v76, 0xbfb8aa3b, v76
	v_exp_f32_e32 v76, v76
	v_and_b32_e32 v81, 0xffff0000, v81
	v_pk_fma_f32 v[80:81], v[6:7], v[80:81], v[14:15]
	v_mul_f32_e32 v74, 0x3fcc422a, v74
	v_add_f32_e32 v76, 1.0, v76
	v_rcp_f32_e32 v86, v76
	v_mul_f32_e32 v76, 0x3d372713, v83
	v_mul_f32_e32 v76, v83, v76
	v_fma_f32 v76, v83, v76, v83
	v_mul_f32_e32 v76, 0x3fcc422a, v76
	v_mul_f32_e32 v76, 0xbfb8aa3b, v76
	v_exp_f32_e32 v76, v76
	v_mul_f32_e32 v74, 0xbfb8aa3b, v74
	v_exp_f32_e32 v74, v74
	v_add_f32_e32 v76, 1.0, v76
	v_rcp_f32_e32 v87, v76
	v_add_f32_e32 v74, 1.0, v74
	v_rcp_f32_e32 v106, v74
	v_mul_f32_e32 v74, 0x3d372713, v105
	v_pk_mul_f32 v[82:83], v[82:83], v[86:87]
	v_mul_f32_e32 v74, v105, v74
	v_pk_mul_f32 v[78:79], v[78:79], v[82:83]
	v_lshlrev_b32_e32 v82, 16, v85
	v_cvt_pk_bf16_f32 v76, v78, v79
	v_lshlrev_b32_e32 v78, 16, v89
	v_and_b32_e32 v79, 0xffff0000, v89
	v_pk_fma_f32 v[78:79], v[18:19], v[78:79], v[58:59]
	v_and_b32_e32 v83, 0xffff0000, v85
	v_pk_fma_f32 v[78:79], v[34:35], v[82:83], v[78:79]
	v_lshlrev_b32_e32 v82, 16, v73
	v_and_b32_e32 v83, 0xffff0000, v73
	v_pk_fma_f32 v[78:79], v[50:51], v[82:83], v[78:79]
	v_lshlrev_b32_e32 v82, 16, v77
	v_and_b32_e32 v83, 0xffff0000, v77
	v_pk_fma_f32 v[80:81], v[38:39], v[82:83], v[80:81]
	v_lshlrev_b32_e32 v82, 16, v69
	v_and_b32_e32 v83, 0xffff0000, v69
	v_pk_fma_f32 v[80:81], v[54:55], v[82:83], v[80:81]
	v_fma_f32 v74, v105, v74, v105
	v_mul_f32_e32 v77, 0x3d372713, v80
	v_mul_f32_e32 v77, v80, v77
	v_fma_f32 v77, v80, v77, v80
	v_mul_f32_e32 v77, 0x3fcc422a, v77
	v_mul_f32_e32 v77, 0xbfb8aa3b, v77
	v_exp_f32_e32 v77, v77
	v_mul_f32_e32 v74, 0x3fcc422a, v74
	v_mul_f32_e32 v74, 0xbfb8aa3b, v74
	v_exp_f32_e32 v74, v74
	v_add_f32_e32 v77, 1.0, v77
	v_rcp_f32_e32 v82, v77
	v_mul_f32_e32 v77, 0x3d372713, v81
	v_mul_f32_e32 v77, v81, v77
	v_fma_f32 v77, v81, v77, v81
	v_mul_f32_e32 v77, 0x3fcc422a, v77
	v_mul_f32_e32 v77, 0xbfb8aa3b, v77
	v_exp_f32_e32 v77, v77
	v_add_f32_e32 v74, 1.0, v74
	v_rcp_f32_e32 v107, v74
	v_add_f32_e32 v77, 1.0, v77
	v_rcp_f32_e32 v83, v77
	v_pk_mul_f32 v[104:105], v[104:105], v[106:107]
	v_pk_mul_f32 v[80:81], v[80:81], v[82:83]
	v_pk_mul_f32 v[102:103], v[102:103], v[104:105]
	v_pk_mul_f32 v[78:79], v[78:79], v[80:81]
	v_cvt_pk_bf16_f32 v74, v102, v103
	v_cvt_pk_bf16_f32 v77, v78, v79
	v_mad_u64_u32 v[78:79], s[22:23], v100, s6, v[90:91]
	global_store_dwordx4 v[78:79], v[74:77], off sc0 sc1
; DI void p8_phase(const Params& p, int layer, char* lds) {
;     ...
;           if (t < 2 || t >= 254) {
;             const int slot = (t < 2) ? t : t - 252;
;             *(u32x4*)(upe + (size_t)(slot * 2) * DFF) = v0;
;             *(u32x4*)(upe + (size_t)(slot * 2 + 1) * DFF) = g0;
;           }
.LBB0_1183:
	s_or_b64 exec, exec, s[8:9]
	s_nop 0
	v_add_u32_e32 v74, 0xffffff22, v64
	v_cmp_gt_u32_e32 vcc, s63, v74
	s_and_saveexec_b64 s[8:9], vcc
	s_cbranch_execz .LBB0_1176
	v_add_u32_e32 v74, 0xfffffe08, v96
	v_cmp_gt_i32_e32 vcc, 2, v100
	s_nop 1
	v_cndmask_b32_e32 v76, v74, v96, vcc
	v_mad_i64_i32 v[74:75], s[22:23], v76, s6, v[92:93]
	s_waitcnt lgkmcnt(1)
	global_store_dwordx4 v[74:75], v[70:73], off sc0 sc1
	s_nop 1
	v_or_b32_e32 v70, 1, v76
	v_mad_i64_i32 v[70:71], s[22:23], v70, s6, v[92:93]
	s_waitcnt lgkmcnt(0)
	global_store_dwordx4 v[70:71], v[66:69], off sc0 sc1
	s_branch .LBB0_1176
